# prep rows: lane^1/^2/^4 exchanges (8-lane reductions, rope partner fetch) via DPP moves instead of ds_bpermute round trips (42 sites)
# speedup vs baseline: 1.0032x; 1.0032x over previous
.LBB0_568:
	s_or_b64 exec, exec, s[54:55]
	s_waitcnt lgkmcnt(2)
	ds_read_b128 v[52:55], v162 offset:16
	ds_read_b128 v[40:43], v162
	s_waitcnt lgkmcnt(0)
	ds_read_b128 v[56:59], v162 offset:6160
	ds_read_b128 v[60:63], v162 offset:6144
	v_lshlrev_b32_e32 v46, 16, v31
	v_and_b32_e32 v47, 0xffff0000, v31
	v_lshlrev_b32_e32 v44, 16, v39
	v_and_b32_e32 v45, 0xffff0000, v39
	v_lshlrev_b32_e32 v50, 16, v35
	v_and_b32_e32 v51, 0xffff0000, v35
	v_and_b32_e32 v39, 0xffff0000, v30
	s_mov_b32 s2, 0x7d30000
	s_waitcnt lgkmcnt(0)
	v_pk_mul_f32 v[46:47], v[58:59], v[46:47]
	s_nop 0
	v_pk_fma_f32 v[48:49], v[54:55], v[44:45], v[46:47]
	ds_read_b128 v[64:67], v162 offset:12304
	ds_read_b128 v[44:47], v162 offset:12288
	v_lshlrev_b32_e32 v54, 16, v38
	v_and_b32_e32 v55, 0xffff0000, v38
	v_lshlrev_b32_e32 v38, 16, v30
	s_waitcnt lgkmcnt(0)
	v_pk_fma_f32 v[48:49], v[66:67], v[50:51], v[48:49]
	s_nop 0
	v_mul_f32_e32 v31, 0xbfb8aa3b, v48
	v_exp_f32_e32 v31, v31
	s_nop 0
	v_add_f32_e32 v31, 1.0, v31
	v_rcp_f32_e32 v50, v31
	v_mul_f32_e32 v31, 0xbfb8aa3b, v49
	v_exp_f32_e32 v31, v31
	s_nop 0
	v_add_f32_e32 v31, 1.0, v31
	v_rcp_f32_e32 v51, v31
	v_pk_mul_f32 v[30:31], v[56:57], v[38:39]
	v_lshlrev_b32_e32 v38, 16, v34
	v_pk_fma_f32 v[30:31], v[52:53], v[54:55], v[30:31]
	v_and_b32_e32 v39, 0xffff0000, v34
	v_lshlrev_b32_e32 v52, 16, v29
	v_and_b32_e32 v53, 0xffff0000, v29
	v_pk_fma_f32 v[30:31], v[64:65], v[38:39], v[30:31]
	v_lshlrev_b32_e32 v38, 16, v37
	v_and_b32_e32 v39, 0xffff0000, v37
	v_pk_mul_f32 v[52:53], v[62:63], v[52:53]
	v_and_b32_e32 v37, 0xffff0000, v28
	v_pk_fma_f32 v[38:39], v[42:43], v[38:39], v[52:53]
	v_lshlrev_b32_e32 v42, 16, v33
	v_and_b32_e32 v43, 0xffff0000, v33
	s_waitcnt lgkmcnt(0)
	v_pk_fma_f32 v[38:39], v[46:47], v[42:43], v[38:39]
	v_lshlrev_b32_e32 v46, 16, v36
	v_mul_f32_e32 v29, 0xbfb8aa3b, v38
	v_exp_f32_e32 v29, v29
	v_and_b32_e32 v47, 0xffff0000, v36
	v_lshlrev_b32_e32 v36, 16, v28
	v_mul_f32_e32 v34, 0xbfb8aa3b, v30
	v_add_f32_e32 v29, 1.0, v29
	v_rcp_f32_e32 v42, v29
	v_mul_f32_e32 v29, 0xbfb8aa3b, v39
	v_exp_f32_e32 v29, v29
	v_mul_f32_e32 v35, 0xbfb8aa3b, v31
	v_exp_f32_e32 v34, v34
	v_exp_f32_e32 v35, v35
	v_add_f32_e32 v29, 1.0, v29
	v_rcp_f32_e32 v43, v29
	v_pk_mul_f32 v[28:29], v[60:61], v[36:37]
	v_lshlrev_b32_e32 v36, 16, v32
	v_pk_fma_f32 v[28:29], v[40:41], v[46:47], v[28:29]
	v_and_b32_e32 v37, 0xffff0000, v32
	v_pk_fma_f32 v[28:29], v[44:45], v[36:37], v[28:29]
	v_add_f32_e32 v34, 1.0, v34
	v_mul_f32_e32 v32, 0xbfb8aa3b, v28
	v_mul_f32_e32 v33, 0xbfb8aa3b, v29
	v_exp_f32_e32 v32, v32
	v_exp_f32_e32 v33, v33
	v_add_f32_e32 v35, 1.0, v35
	v_rcp_f32_e32 v34, v34
	v_add_f32_e32 v32, 1.0, v32
	v_add_f32_e32 v33, 1.0, v33
	v_rcp_f32_e32 v32, v32
	v_rcp_f32_e32 v33, v33
	v_rcp_f32_e32 v35, v35
	v_pk_mul_f32 v[38:39], v[38:39], v[42:43]
	v_pk_mul_f32 v[48:49], v[48:49], v[50:51]
	v_pk_mul_f32 v[28:29], v[28:29], v[32:33]
	v_pk_mul_f32 v[42:43], v[38:39], v[38:39]
	v_pk_mul_f32 v[32:33], v[28:29], v[28:29]
	v_pk_mul_f32 v[30:31], v[30:31], v[34:35]
	v_add_f32_e32 v32, v32, v33
	v_add_f32_e32 v32, v32, v42
	v_pk_mul_f32 v[34:35], v[30:31], v[30:31]
	v_add_f32_e32 v32, v32, v43
	v_add_f32_e32 v32, v32, v34
	v_pk_mul_f32 v[50:51], v[48:49], v[48:49]
	v_add_f32_e32 v32, v32, v35
	v_add_f32_e32 v32, v32, v50
	v_add_f32_e32 v32, v32, v51
	s_nop 1
	v_mov_b32_dpp v33, v32 row_shl:4 row_mask:0xf bank_mask:0x5
	v_mov_b32_dpp v33, v32 row_shr:4 row_mask:0xf bank_mask:0xa
	s_waitcnt lgkmcnt(0)
	v_add_f32_e32 v32, v32, v33
	s_nop 1
	v_mov_b32_dpp v33, v32 quad_perm:[2,3,0,1] row_mask:0xf bank_mask:0xf
	s_waitcnt lgkmcnt(0)
	v_add_f32_e32 v32, v32, v33
	s_nop 1
	v_mov_b32_dpp v33, v32 quad_perm:[1,0,3,2] row_mask:0xf bank_mask:0xf
	s_waitcnt lgkmcnt(0)
	v_add_f32_e32 v32, v32, v33
	v_add_f32_e32 v32, 0x358637bd, v32
	v_rsq_f32_e32 v32, v32
	s_nop 0
	v_mul_f32_e32 v32, 0x3e000000, v32
	v_pk_mul_f32 v[28:29], v[28:29], v[32:33] op_sel_hi:[1,0]
	v_pk_mul_f32 v[34:35], v[38:39], v[32:33] op_sel_hi:[1,0]
	v_pk_mul_f32 v[30:31], v[30:31], v[32:33] op_sel_hi:[1,0]
	v_pk_mul_f32 v[32:33], v[48:49], v[32:33] op_sel_hi:[1,0]
	v_cvt_pk_bf16_f32 v30, v30, v31
	v_cvt_pk_bf16_f32 v31, v32, v33
	v_add_co_u32_e32 v32, vcc, s2, v134
	v_cvt_pk_bf16_f32 v28, v28, v29
	v_cvt_pk_bf16_f32 v29, v34, v35
	v_addc_co_u32_e32 v33, vcc, 0, v135, vcc
	global_store_dwordx4 v[32:33], v[28:31], off
	s_nop 1
	ds_read_b128 v[40:43], v162 offset:2064
	s_nop 0
	ds_read_b128 v[28:31], v162 offset:2048
	ds_read_b128 v[44:47], v162 offset:8208
	ds_read_b128 v[48:51], v162 offset:8192
	v_lshlrev_b32_e32 v34, 16, v23
	v_and_b32_e32 v35, 0xffff0000, v23
	v_lshlrev_b32_e32 v32, 16, v27
	v_and_b32_e32 v33, 0xffff0000, v27
	v_lshlrev_b32_e32 v38, 16, v19
	v_and_b32_e32 v39, 0xffff0000, v19
	v_and_b32_e32 v27, 0xffff0000, v22
	s_mov_b32 s2, 0x8930000
	s_waitcnt lgkmcnt(0)
	v_pk_mul_f32 v[34:35], v[46:47], v[34:35]
	s_nop 0
	v_pk_fma_f32 v[36:37], v[42:43], v[32:33], v[34:35]
	ds_read_b128 v[52:55], v162 offset:14352
	ds_read_b128 v[32:35], v162 offset:14336
	v_lshlrev_b32_e32 v42, 16, v26
	v_and_b32_e32 v43, 0xffff0000, v26
	v_lshlrev_b32_e32 v26, 16, v22
	v_pk_mul_f32 v[22:23], v[44:45], v[26:27]
	v_lshlrev_b32_e32 v26, 16, v18
	v_pk_fma_f32 v[22:23], v[40:41], v[42:43], v[22:23]
	v_and_b32_e32 v27, 0xffff0000, v18
	v_lshlrev_b32_e32 v40, 16, v21
	v_and_b32_e32 v41, 0xffff0000, v21
	s_waitcnt lgkmcnt(0)
	v_pk_mul_f32 v[40:41], v[50:51], v[40:41]
	v_lshlrev_b32_e32 v42, 16, v8
	v_and_b32_e32 v43, 0xffff0000, v8
	v_lshlrev_b32_e32 v8, 16, v9
	v_and_b32_e32 v9, 0xffff0000, v9
	s_waitcnt lgkmcnt(0)
	v_pk_fma_f32 v[36:37], v[54:55], v[38:39], v[36:37]
	s_nop 0
	v_mul_f32_e32 v19, 0xbfb8aa3b, v36
	v_exp_f32_e32 v19, v19
	s_nop 0
	v_add_f32_e32 v19, 1.0, v19
	v_rcp_f32_e32 v38, v19
	v_mul_f32_e32 v19, 0xbfb8aa3b, v37
	v_exp_f32_e32 v19, v19
	s_nop 0
	v_add_f32_e32 v19, 1.0, v19
	v_rcp_f32_e32 v39, v19
	v_pk_fma_f32 v[18:19], v[52:53], v[26:27], v[22:23]
	v_lshlrev_b32_e32 v26, 16, v25
	v_and_b32_e32 v27, 0xffff0000, v25
	v_pk_fma_f32 v[26:27], v[30:31], v[26:27], v[40:41]
	v_lshlrev_b32_e32 v30, 16, v17
	v_and_b32_e32 v31, 0xffff0000, v17
	s_waitcnt lgkmcnt(0)
	v_pk_fma_f32 v[26:27], v[34:35], v[30:31], v[26:27]
	v_lshlrev_b32_e32 v34, 16, v24
	v_mul_f32_e32 v17, 0xbfb8aa3b, v26
	v_exp_f32_e32 v17, v17
	v_and_b32_e32 v35, 0xffff0000, v24
	v_lshlrev_b32_e32 v24, 16, v20
	v_and_b32_e32 v25, 0xffff0000, v20
	v_add_f32_e32 v17, 1.0, v17
	v_rcp_f32_e32 v30, v17
	v_mul_f32_e32 v17, 0xbfb8aa3b, v27
	v_exp_f32_e32 v17, v17
	v_pk_mul_f32 v[20:21], v[48:49], v[24:25]
	v_lshlrev_b32_e32 v24, 16, v16
	v_pk_fma_f32 v[20:21], v[28:29], v[34:35], v[20:21]
	v_add_f32_e32 v17, 1.0, v17
	v_and_b32_e32 v25, 0xffff0000, v16
	v_rcp_f32_e32 v31, v17
	v_pk_fma_f32 v[16:17], v[32:33], v[24:25], v[20:21]
	v_mul_f32_e32 v22, 0xbfb8aa3b, v18
	v_mul_f32_e32 v20, 0xbfb8aa3b, v16
	v_mul_f32_e32 v21, 0xbfb8aa3b, v17
	v_exp_f32_e32 v20, v20
	v_exp_f32_e32 v21, v21
	v_mul_f32_e32 v23, 0xbfb8aa3b, v19
	v_exp_f32_e32 v22, v22
	v_exp_f32_e32 v23, v23
	v_add_f32_e32 v20, 1.0, v20
	v_add_f32_e32 v21, 1.0, v21
	v_rcp_f32_e32 v20, v20
	v_rcp_f32_e32 v21, v21
	v_add_f32_e32 v22, 1.0, v22
	v_add_f32_e32 v23, 1.0, v23
	v_rcp_f32_e32 v22, v22
	v_rcp_f32_e32 v23, v23
	v_pk_mul_f32 v[16:17], v[16:17], v[20:21]
	v_pk_mul_f32 v[26:27], v[26:27], v[30:31]
	v_pk_mul_f32 v[20:21], v[16:17], v[16:17]
	v_pk_mul_f32 v[30:31], v[26:27], v[26:27]
	v_add_f32_e32 v20, v20, v21
	v_pk_mul_f32 v[18:19], v[18:19], v[22:23]
	v_add_f32_e32 v20, v20, v30
	v_pk_mul_f32 v[22:23], v[18:19], v[18:19]
	v_add_f32_e32 v20, v20, v31
	v_pk_mul_f32 v[36:37], v[36:37], v[38:39]
	v_add_f32_e32 v20, v20, v22
	v_pk_mul_f32 v[38:39], v[36:37], v[36:37]
	v_add_f32_e32 v20, v20, v23
	v_add_f32_e32 v20, v20, v38
	v_add_f32_e32 v20, v20, v39
	s_nop 1
	v_mov_b32_dpp v21, v20 row_shl:4 row_mask:0xf bank_mask:0x5
	v_mov_b32_dpp v21, v20 row_shr:4 row_mask:0xf bank_mask:0xa
	v_lshlrev_b32_e32 v40, 16, v12
	v_and_b32_e32 v41, 0xffff0000, v12
	v_lshlrev_b32_e32 v12, 16, v13
	v_and_b32_e32 v13, 0xffff0000, v13
	s_waitcnt lgkmcnt(0)
	v_add_f32_e32 v20, v20, v21
	s_nop 1
	v_mov_b32_dpp v21, v20 quad_perm:[2,3,0,1] row_mask:0xf bank_mask:0xf
	s_waitcnt lgkmcnt(0)
	v_add_f32_e32 v20, v20, v21
	s_nop 1
	v_mov_b32_dpp v21, v20 quad_perm:[1,0,3,2] row_mask:0xf bank_mask:0xf
	s_waitcnt lgkmcnt(0)
	v_add_f32_e32 v20, v20, v21
	v_add_f32_e32 v20, 0x358637bd, v20
	v_rsq_f32_e32 v20, v20
	s_nop 0
	v_pk_mul_f32 v[16:17], v[16:17], v[20:21] op_sel_hi:[1,0]
	v_pk_mul_f32 v[22:23], v[26:27], v[20:21] op_sel_hi:[1,0]
	v_pk_mul_f32 v[18:19], v[18:19], v[20:21] op_sel_hi:[1,0]
	v_pk_mul_f32 v[20:21], v[36:37], v[20:21] op_sel_hi:[1,0]
	v_cvt_pk_bf16_f32 v18, v18, v19
	v_cvt_pk_bf16_f32 v19, v20, v21
	v_add_co_u32_e32 v20, vcc, s2, v134
	v_cvt_pk_bf16_f32 v16, v16, v17
	v_cvt_pk_bf16_f32 v17, v22, v23
	v_addc_co_u32_e32 v21, vcc, 0, v135, vcc
	global_store_dwordx4 v[20:21], v[16:19], off
	s_nop 1
	ds_read_b128 v[16:19], v162 offset:4112
	s_nop 0
	ds_read_b128 v[20:23], v162 offset:4096
	ds_read_b128 v[24:27], v162 offset:10256
	ds_read_b128 v[28:31], v162 offset:10240
	ds_read_b128 v[32:35], v162 offset:16400
	ds_read_b128 v[36:39], v162 offset:16384
	s_waitcnt lgkmcnt(0)
	v_pk_mul_f32 v[28:29], v[28:29], v[42:43]
	s_nop 0
	v_pk_fma_f32 v[20:21], v[20:21], v[40:41], v[28:29]
	v_lshlrev_b32_e32 v28, 16, v4
	v_and_b32_e32 v29, 0xffff0000, v4
	s_waitcnt lgkmcnt(0)
	v_pk_fma_f32 v[20:21], v[36:37], v[28:29], v[20:21]
	v_pk_mul_f32 v[8:9], v[30:31], v[8:9]
	v_mul_f32_e32 v4, 0xbfb8aa3b, v20
	v_exp_f32_e32 v4, v4
	v_pk_fma_f32 v[8:9], v[22:23], v[12:13], v[8:9]
	v_lshlrev_b32_e32 v12, 16, v10
	v_and_b32_e32 v13, 0xffff0000, v10
	v_add_f32_e32 v4, 1.0, v4
	v_rcp_f32_e32 v28, v4
	v_mul_f32_e32 v4, 0xbfb8aa3b, v21
	v_exp_f32_e32 v4, v4
	v_pk_mul_f32 v[12:13], v[24:25], v[12:13]
	v_lshlrev_b32_e32 v10, 16, v11
	v_and_b32_e32 v11, 0xffff0000, v11
	v_add_f32_e32 v4, 1.0, v4
	v_rcp_f32_e32 v29, v4
	v_lshlrev_b32_e32 v4, 16, v5
	v_and_b32_e32 v5, 0xffff0000, v5
	v_pk_fma_f32 v[4:5], v[38:39], v[4:5], v[8:9]
	v_pk_mul_f32 v[10:11], v[26:27], v[10:11]
	v_mul_f32_e32 v8, 0xbfb8aa3b, v4
	v_mul_f32_e32 v9, 0xbfb8aa3b, v5
	v_exp_f32_e32 v8, v8
	v_exp_f32_e32 v9, v9
	v_pk_mul_f32 v[20:21], v[20:21], v[28:29]
	v_add_f32_e32 v8, 1.0, v8
	v_add_f32_e32 v9, 1.0, v9
	v_rcp_f32_e32 v8, v8
	v_rcp_f32_e32 v9, v9
	s_nop 0
	v_pk_mul_f32 v[8:9], v[4:5], v[8:9]
	v_lshlrev_b32_e32 v4, 16, v14
	v_and_b32_e32 v5, 0xffff0000, v14
	v_pk_fma_f32 v[4:5], v[16:17], v[4:5], v[12:13]
	v_lshlrev_b32_e32 v12, 16, v6
	v_and_b32_e32 v13, 0xffff0000, v6
	v_pk_fma_f32 v[4:5], v[32:33], v[12:13], v[4:5]
	s_nop 0
	v_mul_f32_e32 v6, 0xbfb8aa3b, v4
	v_exp_f32_e32 v6, v6
	s_nop 0
	v_add_f32_e32 v6, 1.0, v6
	v_rcp_f32_e32 v12, v6
	v_mul_f32_e32 v6, 0xbfb8aa3b, v5
	v_exp_f32_e32 v6, v6
	s_nop 0
	v_add_f32_e32 v6, 1.0, v6
	v_rcp_f32_e32 v13, v6
	v_lshlrev_b32_e32 v6, 16, v7
	v_and_b32_e32 v7, 0xffff0000, v7
	v_pk_mul_f32 v[12:13], v[4:5], v[12:13]
	v_lshlrev_b32_e32 v4, 16, v15
	v_and_b32_e32 v5, 0xffff0000, v15
	v_pk_fma_f32 v[4:5], v[18:19], v[4:5], v[10:11]
	s_nop 0
	v_pk_fma_f32 v[4:5], v[34:35], v[6:7], v[4:5]
	s_nop 0
	v_mul_f32_e32 v6, 0xbfb8aa3b, v4
	v_mul_f32_e32 v7, 0xbfb8aa3b, v5
	v_exp_f32_e32 v6, v6
	v_exp_f32_e32 v7, v7
	v_add_f32_e32 v6, 1.0, v6
	v_add_f32_e32 v7, 1.0, v7
	v_rcp_f32_e32 v6, v6
	v_rcp_f32_e32 v7, v7
	s_nop 0
	v_pk_mul_f32 v[10:11], v[4:5], v[6:7]
	v_cvt_pk_bf16_f32 v5, v8, v9
	v_add_co_u32_e32 v8, vcc, 0x9530000, v134
	v_cvt_pk_bf16_f32 v4, v20, v21
	v_cvt_pk_bf16_f32 v6, v12, v13
	v_cvt_pk_bf16_f32 v7, v10, v11
	v_addc_co_u32_e32 v9, vcc, 0, v135, vcc
	global_store_dwordx4 v[8:9], v[4:7], off
	s_nop 1

.LBB0_591:
	s_or_b64 exec, exec, s[56:57]
	v_readlane_b32 s84, v254, 52
	v_readlane_b32 s85, v254, 53
	v_lshrrev_b32_e32 v234, 6, v143
	v_and_b32_e32 v235, 63, v0
	v_cndmask_b32_e64 v236, v235, v234, s[44:45]
	v_lshl_or_b32 v236, v236, 6, v75
	v_add_u32_e32 v237, 0x1000, v236
	v_cndmask_b32_e64 v234, v234, v235, s[46:47]
	v_lshlrev_b32_e32 v234, 5, v234
	v_add_u32_e32 v234, 0x2000, v234
	global_load_dwordx4 v[202:205], v237, s[84:85]
	global_load_dwordx4 v[206:209], v237, s[84:85] offset:16
	global_load_dwordx4 v[210:213], v236, s[84:85]
	global_load_dwordx4 v[214:217], v236, s[84:85] offset:16
	global_load_dwordx4 v[218:221], v234, s[84:85] offset:2064
	global_load_dwordx4 v[222:225], v234, s[84:85] offset:2048
	global_load_dwordx4 v[226:229], v234, s[84:85] offset:16
	global_load_dwordx4 v[230:233], v234, s[84:85]
	ds_read_b128 v[66:69], v188 offset:18432
	ds_read_b128 v[134:137], v188 offset:18448
	s_waitcnt vmcnt(11)
	v_lshlrev_b32_e32 v70, 16, v60
	v_and_b32_e32 v71, 0xffff0000, v60
	v_lshlrev_b32_e32 v60, 16, v61
	v_and_b32_e32 v61, 0xffff0000, v61
	v_pk_mul_f32 v[144:145], v[70:71], v[70:71]
	v_pk_mul_f32 v[146:147], v[60:61], v[60:61]
	v_add_f32_e32 v141, v144, v145
	v_lshlrev_b32_e32 v138, 16, v62
	v_and_b32_e32 v139, 0xffff0000, v62
	v_add_f32_e32 v141, v146, v141
	v_pk_mul_f32 v[148:149], v[138:139], v[138:139]
	v_add_f32_e32 v141, v147, v141
	v_and_b32_e32 v64, 0xffff0000, v63
	v_lshlrev_b32_e32 v65, 16, v63
	v_add_f32_e32 v141, v148, v141
	v_cmp_lt_i32_e32 vcc, v185, v182
	v_pk_mul_f32 v[62:63], v[64:65], v[64:65]
	v_add_f32_e32 v141, v149, v141
	v_cndmask_b32_e32 v140, v179, v185, vcc
	v_add_f32_e32 v63, v63, v141
	v_lshlrev_b32_e32 v140, 2, v140
	v_add_f32_e32 v62, v62, v63
	s_nop 1
	v_mov_b32_dpp v63, v62 row_shl:4 row_mask:0xf bank_mask:0x5
	v_mov_b32_dpp v63, v62 row_shr:4 row_mask:0xf bank_mask:0xa
	v_cmp_lt_i32_e32 vcc, v186, v182
	s_waitcnt lgkmcnt(0)
	v_add_f32_e32 v62, v62, v63
	v_cndmask_b32_e32 v141, v179, v186, vcc
	v_lshlrev_b32_e32 v141, 2, v141
	s_nop 1
	v_mov_b32_dpp v63, v62 quad_perm:[2,3,0,1] row_mask:0xf bank_mask:0xf
	v_cmp_lt_i32_e32 vcc, v187, v182
	s_waitcnt lgkmcnt(0)
	v_add_f32_e32 v62, v62, v63
	v_cndmask_b32_e32 v142, v179, v187, vcc
	v_lshlrev_b32_e32 v142, 2, v142
	s_nop 1
	v_mov_b32_dpp v63, v62 quad_perm:[1,0,3,2] row_mask:0xf bank_mask:0xf
	s_waitcnt lgkmcnt(0)
	v_add_f32_e32 v62, v62, v63
	v_fmamk_f32 v62, v62, 0x3c800000, v174
	v_rsq_f32_e32 v62, v62
	s_nop 0
	v_pk_mul_f32 v[70:71], v[62:63], v[70:71] op_sel_hi:[0,1]
	v_pk_mul_f32 v[60:61], v[62:63], v[60:61] op_sel_hi:[0,1]
	v_pk_mul_f32 v[138:139], v[62:63], v[138:139] op_sel_hi:[0,1]
	v_pk_mul_f32 v[144:145], v[62:63], v[64:65] op_sel_hi:[0,1]
	s_waitcnt vmcnt(0) lgkmcnt(0)
	v_pk_mul_f32 v[66:67], v[66:67], v[70:71]
	v_pk_mul_f32 v[64:65], v[68:69], v[60:61]
	s_nop 0
	v_pk_mul_f32 v[62:63], v[134:135], v[138:139]
	v_pk_mul_f32 v[60:61], v[144:145], v[136:137] op_sel:[1,0] op_sel_hi:[0,1]
	s_nop 1
	v_mov_b32_dpp v70, v66 quad_perm:[2,3,0,1] row_mask:0xf bank_mask:0xf
	s_nop 1
	v_mov_b32_dpp v71, v67 quad_perm:[2,3,0,1] row_mask:0xf bank_mask:0xf
	s_nop 1
	v_mov_b32_dpp v136, v64 quad_perm:[2,3,0,1] row_mask:0xf bank_mask:0xf
	s_nop 1
	v_mov_b32_dpp v137, v65 quad_perm:[2,3,0,1] row_mask:0xf bank_mask:0xf
	s_nop 1
	v_mov_b32_dpp v68, v62 quad_perm:[2,3,0,1] row_mask:0xf bank_mask:0xf
	s_nop 1
	v_mov_b32_dpp v69, v63 quad_perm:[2,3,0,1] row_mask:0xf bank_mask:0xf
	s_nop 1
	v_mov_b32_dpp v134, v60 quad_perm:[2,3,0,1] row_mask:0xf bank_mask:0xf
	s_nop 1
	v_mov_b32_dpp v135, v61 quad_perm:[2,3,0,1] row_mask:0xf bank_mask:0xf
	v_lshrrev_b32_e32 v144, 6, v143
	v_and_b32_e32 v145, 63, v0
	v_cndmask_b32_e64 v138, v145, v144, s[44:45]
	s_and_saveexec_b64 s[56:57], s[54:55]
	s_cbranch_execz .LBB0_593
	v_readlane_b32 s80, v254, 48
	v_readlane_b32 s84, v254, 52
	v_readlane_b32 s85, v254, 53
	v_readlane_b32 s81, v254, 49
	v_readlane_b32 s82, v254, 50
	v_readlane_b32 s83, v254, 51
	v_readlane_b32 s86, v254, 54
	v_readlane_b32 s87, v254, 55
	s_waitcnt lgkmcnt(2)
	v_pk_mul_f32 v[68:69], v[206:207], v[68:69]
	v_pk_mul_f32 v[70:71], v[202:203], v[70:71]
	v_pk_mul_f32 v[136:137], v[204:205], v[136:137]
	s_waitcnt lgkmcnt(0)
	v_pk_mul_f32 v[134:135], v[208:209], v[134:135]
	v_cndmask_b32_e64 v137, v137, -v137, s[48:49]
	v_cndmask_b32_e64 v136, v136, -v136, s[48:49]
	v_cndmask_b32_e64 v71, v71, -v71, s[48:49]
	v_cndmask_b32_e64 v70, v70, -v70, s[48:49]
	v_cndmask_b32_e64 v135, v135, -v135, s[48:49]
	v_cndmask_b32_e64 v134, v134, -v134, s[48:49]
	v_cndmask_b32_e64 v69, v69, -v69, s[48:49]
	v_cndmask_b32_e64 v68, v68, -v68, s[48:49]
	v_pk_fma_f32 v[64:65], v[64:65], v[212:213], v[136:137]
	v_pk_fma_f32 v[60:61], v[60:61], v[216:217], v[134:135]
	v_pk_fma_f32 v[66:67], v[66:67], v[210:211], v[70:71]
	v_pk_fma_f32 v[62:63], v[62:63], v[214:215], v[68:69]
.LBB0_593:
	s_or_b64 exec, exec, s[56:57]
	v_readlane_b32 s80, v254, 48
	s_mov_b32 s2, 0x3e38aa3b
	v_readlane_b32 s84, v254, 52
	v_readlane_b32 s85, v254, 53
	v_pk_mul_f32 v[66:67], v[66:67], s[2:3] op_sel_hi:[1,0]
	v_pk_mul_f32 v[64:65], v[64:65], s[2:3] op_sel_hi:[1,0]
	v_pk_mul_f32 v[62:63], v[62:63], s[2:3] op_sel_hi:[1,0]
	s_waitcnt lgkmcnt(2)
	v_pk_mul_f32 v[68:69], v[60:61], s[2:3] op_sel_hi:[1,0]
	s_waitcnt lgkmcnt(0)
	v_lshl_add_u64 v[134:135], s[84:85], 0, v[122:123]
	s_mov_b32 s2, 0x5950000
	v_cvt_pk_bf16_f32 v61, v64, v65
	v_add_co_u32_e32 v64, vcc, s2, v134
	v_cvt_pk_bf16_f32 v60, v66, v67
	v_cvt_pk_bf16_f32 v62, v62, v63
	v_cvt_pk_bf16_f32 v63, v68, v69
	v_addc_co_u32_e32 v65, vcc, 0, v135, vcc
	global_store_dwordx4 v[64:65], v[60:63], off
	s_nop 1
	ds_read_b128 v[60:63], v188 offset:18688
	s_nop 0
	ds_read_b128 v[64:67], v188 offset:18704
	v_lshlrev_b32_e32 v70, 16, v56
	v_and_b32_e32 v71, 0xffff0000, v56
	v_lshlrev_b32_e32 v56, 16, v57
	v_and_b32_e32 v57, 0xffff0000, v57
	v_pk_mul_f32 v[146:147], v[70:71], v[70:71]
	v_pk_mul_f32 v[148:149], v[56:57], v[56:57]
	v_add_f32_e32 v139, v146, v147
	v_lshlrev_b32_e32 v136, 16, v58
	v_and_b32_e32 v137, 0xffff0000, v58
	v_add_f32_e32 v139, v148, v139
	v_pk_mul_f32 v[150:151], v[136:137], v[136:137]
	v_add_f32_e32 v139, v149, v139
	v_and_b32_e32 v68, 0xffff0000, v59
	v_lshlrev_b32_e32 v69, 16, v59
	v_add_f32_e32 v139, v150, v139
	v_pk_mul_f32 v[58:59], v[68:69], v[68:69]
	v_add_f32_e32 v139, v151, v139
	v_add_f32_e32 v59, v59, v139
	v_add_f32_e32 v58, v58, v59
	s_nop 1
	v_mov_b32_dpp v59, v58 row_shl:4 row_mask:0xf bank_mask:0x5
	v_mov_b32_dpp v59, v58 row_shr:4 row_mask:0xf bank_mask:0xa
	v_readlane_b32 s81, v254, 49
	v_readlane_b32 s82, v254, 50
	v_readlane_b32 s83, v254, 51
	v_readlane_b32 s86, v254, 54
	s_waitcnt lgkmcnt(0)
	v_add_f32_e32 v58, v58, v59
	s_nop 1
	v_mov_b32_dpp v59, v58 quad_perm:[2,3,0,1] row_mask:0xf bank_mask:0xf
	v_readlane_b32 s87, v254, 55
	s_waitcnt lgkmcnt(0)
	v_add_f32_e32 v58, v58, v59
	s_nop 1
	v_mov_b32_dpp v59, v58 quad_perm:[1,0,3,2] row_mask:0xf bank_mask:0xf
	s_waitcnt lgkmcnt(0)
	v_add_f32_e32 v58, v58, v59
	v_fmamk_f32 v58, v58, 0x3c800000, v174
	v_rsq_f32_e32 v58, v58
	s_nop 0
	v_pk_mul_f32 v[70:71], v[58:59], v[70:71] op_sel_hi:[0,1]
	v_pk_mul_f32 v[56:57], v[58:59], v[56:57] op_sel_hi:[0,1]
	v_pk_mul_f32 v[136:137], v[58:59], v[136:137] op_sel_hi:[0,1]
	v_pk_mul_f32 v[58:59], v[58:59], v[68:69] op_sel_hi:[0,1]
	s_waitcnt lgkmcnt(0)
	v_pk_mul_f32 v[60:61], v[60:61], v[70:71]
	v_pk_mul_f32 v[62:63], v[62:63], v[56:57]
	s_nop 0
	v_pk_mul_f32 v[56:57], v[64:65], v[136:137]
	v_pk_mul_f32 v[58:59], v[58:59], v[66:67] op_sel:[1,0] op_sel_hi:[0,1]
	s_nop 1
	v_mov_b32_dpp v66, v60 quad_perm:[2,3,0,1] row_mask:0xf bank_mask:0xf
	s_nop 1
	v_mov_b32_dpp v67, v61 quad_perm:[2,3,0,1] row_mask:0xf bank_mask:0xf
	s_nop 1
	v_mov_b32_dpp v70, v62 quad_perm:[2,3,0,1] row_mask:0xf bank_mask:0xf
	s_nop 1
	v_mov_b32_dpp v71, v63 quad_perm:[2,3,0,1] row_mask:0xf bank_mask:0xf
	s_nop 1
	v_mov_b32_dpp v64, v56 quad_perm:[2,3,0,1] row_mask:0xf bank_mask:0xf
	s_nop 1
	v_mov_b32_dpp v65, v57 quad_perm:[2,3,0,1] row_mask:0xf bank_mask:0xf
	s_nop 1
	v_mov_b32_dpp v68, v58 quad_perm:[2,3,0,1] row_mask:0xf bank_mask:0xf
	s_nop 1
	v_mov_b32_dpp v69, v59 quad_perm:[2,3,0,1] row_mask:0xf bank_mask:0xf
	s_and_saveexec_b64 s[56:57], s[54:55]
	s_cbranch_execz .LBB0_595
	v_readlane_b32 s80, v254, 48
	v_readlane_b32 s84, v254, 52
	v_readlane_b32 s85, v254, 53
	v_readlane_b32 s81, v254, 49
	v_readlane_b32 s82, v254, 50
	v_readlane_b32 s83, v254, 51
	v_readlane_b32 s86, v254, 54
	v_readlane_b32 s87, v254, 55
	s_waitcnt lgkmcnt(2)
	v_pk_mul_f32 v[64:65], v[206:207], v[64:65]
	v_pk_mul_f32 v[66:67], v[202:203], v[66:67]
	v_pk_mul_f32 v[70:71], v[204:205], v[70:71]
	s_waitcnt lgkmcnt(0)
	v_pk_mul_f32 v[68:69], v[208:209], v[68:69]
	v_cndmask_b32_e64 v71, v71, -v71, s[48:49]
	v_cndmask_b32_e64 v70, v70, -v70, s[48:49]
	v_cndmask_b32_e64 v67, v67, -v67, s[48:49]
	v_cndmask_b32_e64 v66, v66, -v66, s[48:49]
	v_cndmask_b32_e64 v69, v69, -v69, s[48:49]
	v_cndmask_b32_e64 v68, v68, -v68, s[48:49]
	v_cndmask_b32_e64 v65, v65, -v65, s[48:49]
	v_cndmask_b32_e64 v64, v64, -v64, s[48:49]
	v_pk_fma_f32 v[62:63], v[62:63], v[212:213], v[70:71]
	v_pk_fma_f32 v[58:59], v[58:59], v[216:217], v[68:69]
	v_pk_fma_f32 v[60:61], v[60:61], v[210:211], v[66:67]
	v_pk_fma_f32 v[56:57], v[56:57], v[214:215], v[64:65]

.LBB0_600:
	s_or_b64 exec, exec, s[56:57]
	v_lshlrev_b32_e32 v52, 16, v48
	v_and_b32_e32 v53, 0xffff0000, v48
	v_pk_mul_f32 v[56:57], v[52:53], v[52:53]
	v_lshlrev_b32_e32 v48, 16, v49
	v_and_b32_e32 v49, 0xffff0000, v49
	v_pk_mul_f32 v[58:59], v[48:49], v[48:49]
	v_add_f32_e32 v56, v56, v57
	v_lshlrev_b32_e32 v54, 16, v50
	v_and_b32_e32 v55, 0xffff0000, v50
	v_add_f32_e32 v56, v58, v56
	v_pk_mul_f32 v[60:61], v[54:55], v[54:55]
	v_add_f32_e32 v56, v59, v56
	v_lshlrev_b32_e32 v50, 16, v51
	v_and_b32_e32 v51, 0xffff0000, v51
	v_add_f32_e32 v56, v60, v56
	v_pk_mul_f32 v[62:63], v[50:51], v[50:51]
	v_add_f32_e32 v56, v61, v56
	v_add_f32_e32 v56, v62, v56
	v_cmp_lt_i32_e32 vcc, v180, v182
	v_add_f32_e32 v56, v63, v56
	v_cndmask_b32_e64 v56, 0, v56, s[42:43]
	v_cndmask_b32_e32 v57, v179, v180, vcc
	v_lshlrev_b32_e32 v58, 2, v57
	ds_bpermute_b32 v57, v58, v56
	v_cmp_lt_i32_e32 vcc, v183, v182
	s_waitcnt lgkmcnt(0)
	v_add_f32_e32 v56, v56, v57
	v_cndmask_b32_e32 v57, v179, v183, vcc
	v_lshlrev_b32_e32 v59, 2, v57
	ds_bpermute_b32 v57, v59, v56
	v_cmp_lt_i32_e32 vcc, v184, v182
	s_waitcnt lgkmcnt(0)
	v_add_f32_e32 v56, v56, v57
	v_cndmask_b32_e32 v57, v179, v184, vcc
	v_lshlrev_b32_e32 v60, 2, v57
	ds_bpermute_b32 v57, v60, v56
	s_waitcnt lgkmcnt(0)
	v_add_f32_e32 v56, v56, v57
	s_nop 1
	v_mov_b32_dpp v57, v56 row_shl:4 row_mask:0xf bank_mask:0x5
	v_mov_b32_dpp v57, v56 row_shr:4 row_mask:0xf bank_mask:0xa
	s_waitcnt lgkmcnt(0)
	v_add_f32_e32 v56, v56, v57
	s_nop 1
	v_mov_b32_dpp v57, v56 quad_perm:[2,3,0,1] row_mask:0xf bank_mask:0xf
	s_waitcnt lgkmcnt(0)
	v_add_f32_e32 v56, v56, v57
	s_nop 1
	v_mov_b32_dpp v57, v56 quad_perm:[1,0,3,2] row_mask:0xf bank_mask:0xf
	s_and_saveexec_b64 s[56:57], s[42:43]
	s_cbranch_execz .LBB0_602
	ds_read_b128 v[62:65], v162 offset:18944
	ds_read_b128 v[66:69], v162 offset:18960
	s_waitcnt lgkmcnt(0)
	v_add_f32_e32 v56, v56, v57
	v_fmamk_f32 v56, v56, 0x3b2aaaab, v174
	v_rsq_f32_e32 v56, v56
	v_readlane_b32 s80, v254, 48
	v_readlane_b32 s84, v254, 52
	v_readlane_b32 s85, v254, 53
	v_pk_mul_f32 v[52:53], v[56:57], v[52:53] op_sel_hi:[0,1]
	v_pk_mul_f32 v[48:49], v[56:57], v[48:49] op_sel_hi:[0,1]
	v_pk_mul_f32 v[54:55], v[56:57], v[54:55] op_sel_hi:[0,1]
	v_pk_mul_f32 v[50:51], v[56:57], v[50:51] op_sel_hi:[0,1]
	v_readlane_b32 s81, v254, 49
	v_readlane_b32 s82, v254, 50
	v_readlane_b32 s83, v254, 51
	v_readlane_b32 s86, v254, 54
	v_readlane_b32 s87, v254, 55
	s_waitcnt lgkmcnt(0)
	v_pk_mul_f32 v[52:53], v[52:53], v[62:63]
	v_pk_mul_f32 v[56:57], v[48:49], v[64:65]
	s_nop 0
	v_pk_mul_f32 v[54:55], v[54:55], v[66:67]
	v_pk_mul_f32 v[62:63], v[50:51], v[68:69]
	v_cvt_pk_bf16_f32 v48, v52, v53
	v_cvt_pk_bf16_f32 v49, v56, v57
	v_cvt_pk_bf16_f32 v50, v54, v55
	v_cvt_pk_bf16_f32 v51, v62, v63
	v_lshl_add_u64 v[52:53], s[84:85], 0, v[120:121]
	global_store_dwordx4 v[52:53], v[48:51], off
.LBB0_602:
	s_or_b64 exec, exec, s[56:57]
	s_nop 0
	v_lshlrev_b32_e32 v48, 16, v44
	v_and_b32_e32 v49, 0xffff0000, v44
	v_lshlrev_b32_e32 v54, 16, v47
	v_and_b32_e32 v55, 0xffff0000, v47
	v_lshlrev_b32_e32 v56, 16, v46
	s_waitcnt lgkmcnt(0)
	v_and_b32_e32 v57, 0xffff0000, v46
	v_lshlrev_b32_e32 v46, 16, v45
	v_and_b32_e32 v47, 0xffff0000, v45
	v_pk_mul_f32 v[44:45], v[48:49], v[48:49]
	v_pk_mul_f32 v[62:63], v[46:47], v[46:47]
	v_add_f32_e32 v44, v44, v45
	v_add_f32_e32 v44, v62, v44
	v_pk_mul_f32 v[52:53], v[56:57], v[56:57]
	v_add_f32_e32 v44, v63, v44
	v_add_f32_e32 v44, v52, v44
	v_pk_mul_f32 v[50:51], v[54:55], v[54:55]
	v_add_f32_e32 v44, v53, v44
	v_add_f32_e32 v44, v50, v44
	v_add_f32_e32 v44, v51, v44
	v_cndmask_b32_e64 v44, 0, v44, s[38:39]
	ds_bpermute_b32 v45, v58, v44
	v_mul_i32_i24_e32 v50, 0xa00, v147
	s_movk_i32 s2, 0x1200
	v_add3_u32 v50, v143, v50, s2
	v_ashrrev_i32_e32 v51, 31, v50
	s_waitcnt lgkmcnt(0)
	v_add_f32_e32 v44, v44, v45
	ds_bpermute_b32 v45, v59, v44
	v_cndmask_b32_e64 v53, v1, v51, s[54:55]
	v_cndmask_b32_e64 v52, v0, v50, s[54:55]
	s_waitcnt lgkmcnt(0)
	v_add_f32_e32 v44, v44, v45
	ds_bpermute_b32 v45, v60, v44
	s_waitcnt lgkmcnt(0)
	v_add_f32_e32 v44, v44, v45
	s_nop 1
	v_mov_b32_dpp v45, v44 row_shl:4 row_mask:0xf bank_mask:0x5
	v_mov_b32_dpp v45, v44 row_shr:4 row_mask:0xf bank_mask:0xa
	s_waitcnt lgkmcnt(0)
	v_add_f32_e32 v44, v44, v45
	s_nop 1
	v_mov_b32_dpp v45, v44 quad_perm:[2,3,0,1] row_mask:0xf bank_mask:0xf
	s_waitcnt lgkmcnt(0)
	v_add_f32_e32 v44, v44, v45
	s_nop 1
	v_mov_b32_dpp v45, v44 quad_perm:[1,0,3,2] row_mask:0xf bank_mask:0xf
	s_and_saveexec_b64 s[54:55], s[38:39]
	s_cbranch_execz .LBB0_605
	ds_read_b128 v[58:61], v189 offset:20496
	ds_read_b128 v[62:65], v189 offset:20480
	s_waitcnt lgkmcnt(0)
	v_add_f32_e32 v44, v44, v45
	v_fmamk_f32 v44, v44, 0x3b800000, v174
	v_rsq_f32_e32 v66, v44
	s_nop 0
	v_pk_mul_f32 v[44:45], v[66:67], v[48:49] op_sel_hi:[0,1]
	s_waitcnt lgkmcnt(0)
	v_pk_mul_f32 v[48:49], v[62:63], v[44:45]
	v_pk_mul_f32 v[44:45], v[66:67], v[46:47] op_sel_hi:[0,1]
	v_pk_mul_f32 v[50:51], v[64:65], v[44:45]
	v_pk_mul_f32 v[44:45], v[66:67], v[56:57] op_sel_hi:[0,1]
	v_pk_mul_f32 v[46:47], v[66:67], v[54:55] op_sel_hi:[0,1]
	v_pk_mul_f32 v[44:45], v[58:59], v[44:45]
	v_pk_mul_f32 v[46:47], v[46:47], v[60:61]
	v_lshlrev_b64 v[58:59], 9, v[52:53]
	v_cvt_pk_bf16_f32 v54, v48, v49
	v_cvt_pk_bf16_f32 v55, v50, v51
	v_cvt_pk_bf16_f32 v56, v44, v45
	v_cvt_pk_bf16_f32 v57, v46, v47
	v_lshl_add_u64 v[58:59], v[88:89], 0, v[58:59]
	global_store_dwordx4 v[58:59], v[54:57], off
	s_and_b64 exec, exec, s[52:53]
	s_cbranch_execz .LBB0_605
	v_readlane_b32 s2, v254, 61
	v_readlane_b32 s3, v254, 62
	v_lshlrev_b32_e32 v56, 10, v143
	v_lshl_add_u32 v54, v146, 1, s2
	v_ashrrev_i32_e32 v55, 31, v54
	v_readlane_b32 s2, v253, 28
	v_lshlrev_b64 v[54:55], 18, v[54:55]
	v_readlane_b32 s3, v253, 29
	v_mov_b32_e32 v57, v2
	s_nop 0
	v_lshl_add_u64 v[54:55], s[2:3], 0, v[54:55]
	v_lshl_add_u64 v[54:55], v[54:55], 0, v[56:57]
	v_lshlrev_b32_e32 v56, 2, v72
	v_lshl_add_u64 v[54:55], v[54:55], 0, v[56:57]
	global_store_dwordx4 v[54:55], v[48:51], off
	global_store_dwordx4 v[54:55], v[44:47], off offset:16
.LBB0_605:
	s_or_b64 exec, exec, s[54:55]
	s_nop 0
	v_lshlrev_b32_e32 v44, 16, v40
	s_waitcnt lgkmcnt(0)
	v_and_b32_e32 v45, 0xffff0000, v40
	v_lshlrev_b32_e32 v46, 16, v41
	v_and_b32_e32 v47, 0xffff0000, v41
	v_lshlrev_b32_e32 v40, 16, v42
	v_and_b32_e32 v41, 0xffff0000, v42
	v_lshlrev_b32_e32 v42, 16, v43
	v_and_b32_e32 v43, 0xffff0000, v43
	s_nop 1
	v_mov_b32_dpp v48, v44 quad_perm:[1,0,3,2] row_mask:0xf bank_mask:0xf
	s_nop 1
	v_mov_b32_dpp v49, v45 quad_perm:[1,0,3,2] row_mask:0xf bank_mask:0xf
	s_nop 1
	v_mov_b32_dpp v50, v46 quad_perm:[1,0,3,2] row_mask:0xf bank_mask:0xf
	s_nop 1
	v_mov_b32_dpp v51, v47 quad_perm:[1,0,3,2] row_mask:0xf bank_mask:0xf
	s_nop 1
	v_mov_b32_dpp v54, v40 quad_perm:[1,0,3,2] row_mask:0xf bank_mask:0xf
	s_nop 1
	v_mov_b32_dpp v55, v41 quad_perm:[1,0,3,2] row_mask:0xf bank_mask:0xf
	s_nop 1
	v_mov_b32_dpp v56, v42 quad_perm:[1,0,3,2] row_mask:0xf bank_mask:0xf
	s_nop 1
	v_mov_b32_dpp v57, v43 quad_perm:[1,0,3,2] row_mask:0xf bank_mask:0xf
	s_and_saveexec_b64 s[20:21], s[52:53]
	s_xor_b64 s[54:55], exec, s[20:21]
	s_cbranch_execnz .LBB0_608
	s_andn2_saveexec_b64 s[54:55], s[54:55]
	s_cbranch_execnz .LBB0_609
